# s5_fill gather and Toeplitz loops software-pipelined one trip ahead (S5 chain shorter)
# baseline (speedup 1.0000x reference)
; __device__ __forceinline__ unsigned pk2(float lo, float hi) { f32x2_t v = {lo, hi}; bf16x2_t b = __builtin_convertvector(v, bf16x2_t); return __builtin_bit_cast(unsigned, b); }
; __device__ void s5_fill(int swave, const Params& p, int vb, int nvb) {
;     ...
;   for (int it = gtid; it < TOK * 16; it += gsz) {
;     const int g = it & 15, token = it >> 4;
;     const uint4* s = (const uint4*)(P + (size_t)token * ODD_IN + O_SU + g * 16);
;     uint4* d = (uint4*)(U2 + ((size_t)g * 512 + (token >> 6)) * 1280 + (token & 63) * 16);
;     d[0] = s[0]; d[1] = s[1];
;   }
;   for (int it = gtid; it < 16 * 1024 * 128; it += gsz) {
;     const int half = it & 1, jj = (it >> 1) & 63, pp = (it >> 7) & 15, t = (it >> 11) & 63, g = it >> 17;
;     const float4* s = (const float4*)(Ktab + ((size_t)g * 127 + (t - jj + 63)) * 256 + pp * 16 + half * 8);
;     const float4 a = s[0], bq = s[1];
;     uint4 o; o.x = pk2(a.x, a.y); o.y = pk2(a.z, a.w); o.z = pk2(bq.x, bq.y); o.w = pk2(bq.z, bq.w);
;     *(uint4*)(TRt + ((size_t)g * 1024 + t * 16 + pp) * 1280 + jj * 16 + half * 8) = o;
;   }
.LBB0_101:
	v_writelane_b32 v246, s10, 7
	v_mov_b32_e32 v0, v147
	s_lshl_b32 s0, s54, 9
	v_writelane_b32 v246, s11, 8
	s_barrier
	v_writelane_b32 v246, s0, 9
	v_add_u32_e32 v1, s0, v0
	s_mov_b32 s0, 0x80000
	s_mov_b64 s[6:7], 0
	s_mov_b64 s[10:11], 0
	s_mov_b64 s[2:3], 0
	s_mov_b64 s[4:5], 0
	v_cmp_gt_i32_e32 vcc, s0, v1
	s_and_saveexec_b64 s[0:1], vcc
	s_mov_b64 s[16:17], 0xc001400
	s_cbranch_execz .LBB0_104
	v_readlane_b32 s12, v248, 8
	v_readlane_b32 s14, v248, 10
	v_readlane_b32 s15, v248, 11
	s_add_u32 s6, s14, s6
	s_addc_u32 s7, s15, s7
	s_add_u32 s9, s14, s10
	s_addc_u32 s11, s15, s11
	v_and_b32_e32 v0, 15, v0
	v_readlane_b32 s13, v248, 9
	s_add_u32 s10, s9, 0xa000000
	v_lshlrev_b32_e32 v2, 4, v0
	s_addc_u32 s11, s11, 0
	v_lshlrev_b32_e32 v0, 9, v0
	s_mov_b64 s[12:13], 0
	v_lshlrev_b32_e32 v2, 1, v2
	v_mov_b32_e32 v4, v1
	v_ashrrev_i32_e32 v30, 4, v4
	v_mov_b64_e32 v[28:29], s[6:7]
	v_mad_i64_i32 v[28:29], s[14:15], v30, s55, v[28:29]
	v_lshl_add_u64 v[28:29], v[28:29], 0, v[2:3]
	v_add_co_u32_e32 v28, vcc, 0xc001000, v28
	s_nop 1
	v_addc_co_u32_e32 v29, vcc, 0, v29, vcc
	global_load_dwordx4 v[20:23], v[28:29], off offset:1024
	global_load_dwordx4 v[24:27], v[28:29], off offset:1040
	s_mov_b32 s9, 0x7ffff
	s_waitcnt vmcnt(0)
.LBB0_103:
	v_ashrrev_i32_e32 v5, 10, v4
	v_add_u32_e32 v5, v5, v0
	v_mul_hi_i32_i24_e32 v9, 0xa00, v5
	v_mul_i32_i24_e32 v8, 0xa00, v5
	v_and_b32_e32 v5, 0x3f0, v4
	v_lshl_add_u64 v[8:9], s[10:11], 0, v[8:9]
	v_lshlrev_b32_e32 v12, 1, v5
	v_mov_b32_e32 v13, v3
	v_lshl_add_u64 v[12:13], v[8:9], 0, v[12:13]
	v_mov_b32_e32 v6, v20
	v_mov_b32_e32 v7, v21
	v_mov_b32_e32 v8, v22
	v_mov_b32_e32 v9, v23
	v_mov_b32_e32 v14, v24
	v_mov_b32_e32 v15, v25
	v_mov_b32_e32 v16, v26
	v_mov_b32_e32 v17, v27
	v_add_u32_e32 v4, s96, v4
	v_cmp_ge_i32_e32 vcc, s9, v4
	s_and_saveexec_b64 s[18:19], vcc
	s_cbranch_execz .Lgath_nopf
	v_ashrrev_i32_e32 v30, 4, v4
	v_mov_b64_e32 v[28:29], s[6:7]
	v_mad_i64_i32 v[28:29], s[14:15], v30, s55, v[28:29]
	v_lshl_add_u64 v[28:29], v[28:29], 0, v[2:3]
	v_add_co_u32_e32 v28, vcc, 0xc001000, v28
	s_nop 1
	v_addc_co_u32_e32 v29, vcc, 0, v29, vcc
	global_load_dwordx4 v[20:23], v[28:29], off offset:1024
	global_load_dwordx4 v[24:27], v[28:29], off offset:1040
.Lgath_nopf:
	s_or_b64 exec, exec, s[18:19]
	v_cmp_lt_i32_e32 vcc, s9, v4
	s_or_b64 s[12:13], vcc, s[12:13]
	global_store_dwordx4 v[12:13], v[6:9], off
	global_store_dwordx4 v[12:13], v[14:17], off offset:16
	s_waitcnt vmcnt(2)
	s_andn2_b64 exec, exec, s[12:13]
	s_cbranch_execnz .LBB0_103
.LBB0_104:
	s_or_b64 exec, exec, s[0:1]
	s_mov_b32 s0, 0x200000
	v_cmp_gt_i32_e32 vcc, s0, v1
	s_and_saveexec_b64 s[0:1], vcc
	v_readlane_b32 s16, v247, 13
	s_movk_i32 s17, 0xa00
	s_cbranch_execz .LBB0_107
	v_readlane_b32 s12, v248, 8
	v_readlane_b32 s14, v248, 10
	v_readlane_b32 s15, v248, 11
	s_add_u32 s2, s14, s2
	s_addc_u32 s3, s15, s3
	s_add_u32 s2, s2, 0x1b9a0000
	s_addc_u32 s3, s3, 0
	s_add_u32 s4, s14, s4
	s_addc_u32 s5, s15, s5
	s_add_u32 s4, s4, 0x1e9a0000
	s_addc_u32 s5, s5, 0
	v_lshlrev_b32_e32 v0, 3, v1
	s_mov_b64 s[6:7], 0
	v_readlane_b32 s13, v248, 9
	v_bfe_u32 v30, v1, 1, 6
	v_bfe_u32 v31, v1, 11, 6
	v_ashrrev_i32_e32 v32, 17, v1
	v_mul_hi_i32_i24_e32 v29, 0x7f, v32
	v_mul_i32_i24_e32 v28, 0x7f, v32
	v_xad_u32 v2, v30, 63, v31
	v_lshl_add_u64 v[28:29], v[28:29], 0, v[2:3]
	v_bfe_u32 v33, v1, 7, 4
	v_lshlrev_b64 v[28:29], 10, v[28:29]
	v_lshl_add_u64 v[28:29], s[4:5], 0, v[28:29]
	v_lshlrev_b32_e32 v2, 6, v33
	v_and_b32_e32 v34, 8, v0
	v_lshl_add_u64 v[28:29], v[28:29], 0, v[2:3]
	v_lshlrev_b32_e32 v2, 2, v34
	v_lshl_add_u64 v[28:29], v[28:29], 0, v[2:3]
	global_load_dwordx4 v[20:23], v[28:29], off offset:16
	global_load_dwordx4 v[24:27], v[28:29], off
	s_mov_b32 s9, 0x1fffff
	s_waitcnt vmcnt(0)
.LBB0_106:
	v_bfe_u32 v12, v1, 1, 6
	v_bfe_u32 v14, v1, 11, 6
	v_ashrrev_i32_e32 v15, 17, v1
	v_bfe_u32 v13, v1, 7, 4
	v_and_b32_e32 v16, 8, v0
	v_mov_b32_e32 v4, v20
	v_mov_b32_e32 v5, v21
	v_mov_b32_e32 v6, v22
	v_mov_b32_e32 v7, v23
	v_mov_b32_e32 v8, v24
	v_mov_b32_e32 v9, v25
	v_mov_b32_e32 v10, v26
	v_mov_b32_e32 v11, v27
	v_add_u32_e32 v1, s96, v1
	v_add_u32_e32 v0, s16, v0
	v_cmp_ge_i32_e32 vcc, s9, v1
	s_and_saveexec_b64 s[12:13], vcc
	s_cbranch_execz .Lfill_nopf
	v_bfe_u32 v30, v1, 1, 6
	v_bfe_u32 v31, v1, 11, 6
	v_ashrrev_i32_e32 v32, 17, v1
	v_mul_hi_i32_i24_e32 v29, 0x7f, v32
	v_mul_i32_i24_e32 v28, 0x7f, v32
	v_xad_u32 v2, v30, 63, v31
	v_lshl_add_u64 v[28:29], v[28:29], 0, v[2:3]
	v_bfe_u32 v33, v1, 7, 4
	v_lshlrev_b64 v[28:29], 10, v[28:29]
	v_lshl_add_u64 v[28:29], s[4:5], 0, v[28:29]
	v_lshlrev_b32_e32 v2, 6, v33
	v_and_b32_e32 v34, 8, v0
	v_lshl_add_u64 v[28:29], v[28:29], 0, v[2:3]
	v_lshlrev_b32_e32 v2, 2, v34
	v_lshl_add_u64 v[28:29], v[28:29], 0, v[2:3]
	global_load_dwordx4 v[20:23], v[28:29], off offset:16
	global_load_dwordx4 v[24:27], v[28:29], off
.Lfill_nopf:
	s_or_b64 exec, exec, s[12:13]
	v_cmp_lt_i32_e32 vcc, s9, v1
	s_or_b64 s[6:7], vcc, s[6:7]
	v_lshlrev_b32_e32 v2, 10, v15
	v_cvt_pk_bf16_f32 v8, v8, v9
	v_cvt_pk_bf16_f32 v9, v10, v11
	v_cvt_pk_bf16_f32 v10, v4, v5
	v_lshlrev_b32_e32 v4, 4, v14
	v_or3_b32 v2, v2, v4, v13
	v_mov_b64_e32 v[4:5], s[2:3]
	v_mad_i64_i32 v[4:5], s[10:11], v2, s17, v[4:5]
	v_lshlrev_b32_e32 v2, 5, v12
	v_lshl_add_u64 v[4:5], v[4:5], 0, v[2:3]
	v_lshlrev_b32_e32 v2, 1, v16
	v_cvt_pk_bf16_f32 v11, v6, v7
	v_lshl_add_u64 v[4:5], v[4:5], 0, v[2:3]
	global_store_dwordx4 v[4:5], v[8:11], off
	s_waitcnt vmcnt(1)
	s_andn2_b64 exec, exec, s[6:7]
	s_cbranch_execnz .LBB0_106
